# row pass: batch the split-K slab loads of ctx rows (counted vmcnt) instead of serialized load-wait chains
# baseline (speedup 1.0000x reference)
; #define LAS __attribute__((address_space(3)))
; __device__ __forceinline__ unsigned xb_add(unsigned* p, unsigned v) { return __hip_atomic_fetch_add(p, v, __ATOMIC_RELAXED, __HIP_MEMORY_SCOPE_AGENT); }
; __device__ __forceinline__ unsigned xb_xcc_id() { return (unsigned)__builtin_amdgcn_s_getreg((3 << 11) | 20) & 0xFu; }
; __device__ __forceinline__ XcdBarrier xcd_barrier_post(unsigned* bar, volatile LAS unsigned* st) {
;     XcdBarrier b; b.bar = bar; b.x = xb_xcc_id(); b.st = st;
;     if (threadIdx.x == 0) (void)xb_add(&bar[XB_XCNT(b.x)], 1u);
;     return b;
; __global__ void __launch_bounds__(NTHREADS, 2) mega_fwd(Params P) {
;     ...
;     { volatile LAS unsigned* st0 = (volatile LAS unsigned*)(ldsl + RING_BYTES + 2048); if (threadIdx.x < 2) st0[threadIdx.x] = 0u; __syncthreads(); }
;     const unsigned xbar_x = xcd_barrier_post(ctl + 4096, (volatile LAS unsigned*)(ldsl + RING_BYTES + 2048)).x;
_Z8mega_fwd6Params:
	s_mov_b32 s100, 0x200000
	s_mov_b32 s101, 0
	s_load_dwordx8 s[72:79], s[0:1], 0xa0
	s_load_dwordx8 s[4:11], s[0:1], 0x80
	s_load_dword s36, s[0:1], 0xc0
	s_mov_b32 s70, s2
	s_add_u32 s2, s0, 0xb8
	v_and_b32_e32 v214, 0x3ff, v0
	s_waitcnt lgkmcnt(0)
	v_writelane_b32 v253, s4, 0
	s_addc_u32 s3, s1, 0
	v_cmp_gt_u32_e32 vcc, 2, v214
	v_writelane_b32 v253, s5, 1
	v_writelane_b32 v253, s6, 2
	v_writelane_b32 v253, s7, 3
	v_writelane_b32 v253, s8, 4
	v_writelane_b32 v253, s9, 5
	v_writelane_b32 v253, s10, 6
	v_writelane_b32 v253, s11, 7
	s_and_saveexec_b64 s[4:5], vcc
	v_lshl_add_u32 v1, v214, 2, 0
	v_add_u32_e32 v1, 0x20800, v1
	v_mov_b32_e32 v2, 0
	ds_write_b32 v1, v2
	s_or_b64 exec, exec, s[4:5]
	s_mov_b64 s[6:7], s[76:77]
	s_waitcnt lgkmcnt(0)
	s_barrier
	s_getreg_b32 s4, hwreg(HW_REG_XCC_ID, 0, 4)
	s_and_b32 s4, s4, 15
	v_writelane_b32 v253, s4, 8
	v_cmp_eq_u32_e64 s[62:63], 0, v214
	s_and_saveexec_b64 s[4:5], s[62:63]
	s_cbranch_execz .LBB0_4
	v_readlane_b32 s8, v253, 8
	s_lshl_b32 s8, s8, 8
	s_add_u32 s6, s6, s8
	s_addc_u32 s7, s7, 0
	v_mov_b32_e32 v1, s6
	v_add_co_u32_e32 v2, vcc, 0x4000, v1
	v_mov_b32_e32 v1, s7
	s_nop 0
	v_addc_co_u32_e32 v3, vcc, 0, v1, vcc
	v_mov_b32_e32 v1, 1
	flat_atomic_add v[2:3], v1 offset:1024

; __device__ __forceinline__ void row_pass(const Params& P, int l, int mode, LAS float* pl) {
;     ...
;                     const int nsl = (mode == 1) ? 3 : 11;
; #pragma unroll
;                     for (int j = 0; j < 4; ++j) { const float* yq = y32 + (size_t)(b * CTXL + (w - SEQ)) * DM + 4 * lane + 256 * j; f32x4 a = *(const f32x4*)yq;
;                         for (int sl = 1; sl < nsl; ++sl) a = a + *(const f32x4*)(yq + (size_t)sl * 512 * DM);
;                         yv[r][j] = a; }
.LBB0_1030:
	s_cmpk_lt_i32 s14, 0x2000
	s_cselect_b64 s[0:1], -1, 0
	s_cmpk_gt_i32 s14, 0x1fff
	s_mov_b64 s[4:5], -1
	s_cbranch_scc0 .LBB0_1032
	s_lshl_b32 s4, s18, 8
	s_add_i32 s4, s14, s4
	s_addk_i32 s4, 0xe000
	s_ashr_i32 s5, s4, 31
	s_lshl_b64 s[4:5], s[4:5], 12
	v_lshl_add_u64 v[144:145], v[104:105], 0, s[4:5]
	v_add_co_u32_e32 v146, vcc, 0x200000, v144
	s_mov_b64 s[4:5], 0
	s_nop 0
	v_addc_co_u32_e32 v147, vcc, 0, v145, vcc
	v_add_co_u32_e32 v148, vcc, 0x400000, v144
	s_nop 1
	v_addc_co_u32_e32 v149, vcc, 0, v145, vcc
	global_load_dwordx4 v[70:73], v[144:145], off
	global_load_dwordx4 v[160:163], v[146:147], off
	global_load_dwordx4 v[164:167], v[148:149], off
	global_load_dwordx4 v[74:77], v[144:145], off offset:1024
	global_load_dwordx4 v[168:171], v[146:147], off offset:1024
	global_load_dwordx4 v[172:175], v[148:149], off offset:1024
	global_load_dwordx4 v[82:85], v[144:145], off offset:2048
	global_load_dwordx4 v[176:179], v[146:147], off offset:2048
	global_load_dwordx4 v[180:183], v[148:149], off offset:2048
	global_load_dwordx4 v[78:81], v[144:145], off offset:3072
	global_load_dwordx4 v[184:187], v[146:147], off offset:3072
	global_load_dwordx4 v[188:191], v[148:149], off offset:3072
	s_waitcnt vmcnt(10)
	v_pk_add_f32 v[70:71], v[70:71], v[160:161]
	v_pk_add_f32 v[72:73], v[72:73], v[162:163]
	s_waitcnt vmcnt(9)
	v_pk_add_f32 v[70:71], v[70:71], v[164:165]
	v_pk_add_f32 v[72:73], v[72:73], v[166:167]
	s_waitcnt vmcnt(7)
	v_pk_add_f32 v[74:75], v[74:75], v[168:169]
	v_pk_add_f32 v[76:77], v[76:77], v[170:171]
	s_waitcnt vmcnt(6)
	v_pk_add_f32 v[74:75], v[74:75], v[172:173]
	v_pk_add_f32 v[76:77], v[76:77], v[174:175]
	s_waitcnt vmcnt(4)
	v_pk_add_f32 v[82:83], v[82:83], v[176:177]
	v_pk_add_f32 v[84:85], v[84:85], v[178:179]
	s_waitcnt vmcnt(3)
	v_pk_add_f32 v[82:83], v[82:83], v[180:181]
	v_pk_add_f32 v[84:85], v[84:85], v[182:183]
	s_waitcnt vmcnt(1)
	v_pk_add_f32 v[78:79], v[78:79], v[184:185]
	v_pk_add_f32 v[80:81], v[80:81], v[186:187]
	s_waitcnt vmcnt(0)
	v_pk_add_f32 v[78:79], v[78:79], v[188:189]
	v_pk_add_f32 v[80:81], v[80:81], v[190:191]

; __device__ __forceinline__ void row_pass(const Params& P, int l, int mode, LAS float* pl) {
;     ...
;                     const int nsl = (mode == 1) ? 3 : 11;
; #pragma unroll
;                     for (int j = 0; j < 4; ++j) { const float* yq = y32 + (size_t)(b * CTXL + (w - SEQ)) * DM + 4 * lane + 256 * j; f32x4 a = *(const f32x4*)yq;
;                         for (int sl = 1; sl < nsl; ++sl) a = a + *(const f32x4*)(yq + (size_t)sl * 512 * DM);
;                         yv[r][j] = a; }
.LBB0_1038:
	s_cmpk_lt_i32 s10, 0x2000
	s_cselect_b64 s[16:17], -1, 0
	s_mov_b64 s[4:5], -1
	s_and_b64 vcc, exec, s[16:17]
	s_cbranch_vccnz .LBB0_1040
	s_lshl_b32 s4, s19, 8
	s_add_i32 s4, s10, s4
	s_addk_i32 s4, 0xe000
	s_ashr_i32 s5, s4, 31
	s_lshl_b64 s[4:5], s[4:5], 12
	v_lshl_add_u64 v[152:153], v[104:105], 0, s[4:5]
	v_add_co_u32_e32 v154, vcc, 0x200000, v152
	s_mov_b64 s[4:5], 0
	s_nop 0
	v_addc_co_u32_e32 v155, vcc, 0, v153, vcc
	v_add_co_u32_e32 v156, vcc, 0x400000, v152
	s_nop 1
	v_addc_co_u32_e32 v157, vcc, 0, v153, vcc
	global_load_dwordx4 v[86:89], v[152:153], off
	global_load_dwordx4 v[160:163], v[154:155], off
	global_load_dwordx4 v[164:167], v[156:157], off
	global_load_dwordx4 v[90:93], v[152:153], off offset:1024
	global_load_dwordx4 v[168:171], v[154:155], off offset:1024
	global_load_dwordx4 v[172:175], v[156:157], off offset:1024
	global_load_dwordx4 v[98:101], v[152:153], off offset:2048
	global_load_dwordx4 v[176:179], v[154:155], off offset:2048
	global_load_dwordx4 v[180:183], v[156:157], off offset:2048
	global_load_dwordx4 v[94:97], v[152:153], off offset:3072
	global_load_dwordx4 v[184:187], v[154:155], off offset:3072
	global_load_dwordx4 v[188:191], v[156:157], off offset:3072
	s_waitcnt vmcnt(10)
	v_pk_add_f32 v[86:87], v[86:87], v[160:161]
	v_pk_add_f32 v[88:89], v[88:89], v[162:163]
	s_waitcnt vmcnt(9)
	v_pk_add_f32 v[86:87], v[86:87], v[164:165]
	v_pk_add_f32 v[88:89], v[88:89], v[166:167]
	s_waitcnt vmcnt(7)
	v_pk_add_f32 v[90:91], v[90:91], v[168:169]
	v_pk_add_f32 v[92:93], v[92:93], v[170:171]
	s_waitcnt vmcnt(6)
	v_pk_add_f32 v[90:91], v[90:91], v[172:173]
	v_pk_add_f32 v[92:93], v[92:93], v[174:175]
	s_waitcnt vmcnt(4)
	v_pk_add_f32 v[98:99], v[98:99], v[176:177]
	v_pk_add_f32 v[100:101], v[100:101], v[178:179]
	s_waitcnt vmcnt(3)
	v_pk_add_f32 v[98:99], v[98:99], v[180:181]
	v_pk_add_f32 v[100:101], v[100:101], v[182:183]
	s_waitcnt vmcnt(1)
	v_pk_add_f32 v[94:95], v[94:95], v[184:185]
	v_pk_add_f32 v[96:97], v[96:97], v[186:187]
	s_waitcnt vmcnt(0)
	v_pk_add_f32 v[94:95], v[94:95], v[188:189]
	v_pk_add_f32 v[96:97], v[96:97], v[190:191]

; __device__ __forceinline__ void row_pass(const Params& P, int l, int mode, LAS float* pl) {
;     ...
;                     const int nsl = (mode == 1) ? 3 : 11;
; #pragma unroll
;                     for (int j = 0; j < 4; ++j) { const float* yq = y32 + (size_t)(b * CTXL + (w - SEQ)) * DM + 4 * lane + 256 * j; f32x4 a = *(const f32x4*)yq;
;                         for (int sl = 1; sl < nsl; ++sl) a = a + *(const f32x4*)(yq + (size_t)sl * 512 * DM);
;                         yv[r][j] = a; }
.LBB0_1293:
	s_cmpk_lt_i32 s20, 0x2000
	s_cselect_b64 s[0:1], -1, 0
	s_cmpk_gt_i32 s20, 0x1fff
	s_mov_b64 s[8:9], -1
	s_cbranch_scc0 .LBB0_1295
	s_lshl_b32 s8, s21, 8
	s_add_i32 s8, s20, s8
	s_addk_i32 s8, 0xe000
	s_ashr_i32 s9, s8, 31
	s_lshl_b64 s[8:9], s[8:9], 12
	v_lshl_add_u64 v[78:79], v[144:145], 0, s[8:9]
	s_mov_b64 s[8:9], 0
	v_lshl_add_u64 v[80:81], v[78:79], 0, s[100:101]
	v_lshl_add_u64 v[134:135], v[80:81], 0, s[100:101]
	v_lshl_add_u64 v[136:137], v[134:135], 0, s[100:101]
	v_lshl_add_u64 v[138:139], v[136:137], 0, s[100:101]
	v_lshl_add_u64 v[140:141], v[138:139], 0, s[100:101]
	v_lshl_add_u64 v[174:175], v[140:141], 0, s[100:101]
	v_lshl_add_u64 v[176:177], v[174:175], 0, s[100:101]
	v_lshl_add_u64 v[178:179], v[176:177], 0, s[100:101]
	v_lshl_add_u64 v[180:181], v[178:179], 0, s[100:101]
	v_lshl_add_u64 v[182:183], v[180:181], 0, s[100:101]
	global_load_dwordx4 v[70:73], v[78:79], off
	global_load_dwordx4 v[86:89], v[80:81], off
	global_load_dwordx4 v[90:93], v[134:135], off
	global_load_dwordx4 v[94:97], v[136:137], off
	global_load_dwordx4 v[98:101], v[138:139], off
	global_load_dwordx4 v[102:105], v[140:141], off
	global_load_dwordx4 v[106:109], v[174:175], off
	global_load_dwordx4 v[110:113], v[176:177], off
	global_load_dwordx4 v[114:117], v[178:179], off
	global_load_dwordx4 v[118:121], v[180:181], off
	global_load_dwordx4 v[122:125], v[182:183], off
	global_load_dwordx4 v[74:77], v[78:79], off offset:1024
	global_load_dwordx4 v[184:187], v[80:81], off offset:1024
	global_load_dwordx4 v[188:191], v[134:135], off offset:1024
	global_load_dwordx4 v[198:201], v[136:137], off offset:1024
	global_load_dwordx4 v[202:205], v[138:139], off offset:1024
	global_load_dwordx4 v[206:209], v[140:141], off offset:1024
	global_load_dwordx4 v[224:227], v[174:175], off offset:1024
	global_load_dwordx4 v[228:231], v[176:177], off offset:1024
	global_load_dwordx4 v[232:235], v[178:179], off offset:1024
	global_load_dwordx4 v[236:239], v[180:181], off offset:1024
	global_load_dwordx4 v[240:243], v[182:183], off offset:1024
	s_waitcnt vmcnt(20)
	v_pk_add_f32 v[70:71], v[70:71], v[86:87]
	v_pk_add_f32 v[72:73], v[72:73], v[88:89]
	s_waitcnt vmcnt(19)
	v_pk_add_f32 v[70:71], v[70:71], v[90:91]
	v_pk_add_f32 v[72:73], v[72:73], v[92:93]
	s_waitcnt vmcnt(18)
	v_pk_add_f32 v[70:71], v[70:71], v[94:95]
	v_pk_add_f32 v[72:73], v[72:73], v[96:97]
	s_waitcnt vmcnt(17)
	v_pk_add_f32 v[70:71], v[70:71], v[98:99]
	v_pk_add_f32 v[72:73], v[72:73], v[100:101]
	s_waitcnt vmcnt(16)
	v_pk_add_f32 v[70:71], v[70:71], v[102:103]
	v_pk_add_f32 v[72:73], v[72:73], v[104:105]
	s_waitcnt vmcnt(15)
	v_pk_add_f32 v[70:71], v[70:71], v[106:107]
	v_pk_add_f32 v[72:73], v[72:73], v[108:109]
	s_waitcnt vmcnt(14)
	v_pk_add_f32 v[70:71], v[70:71], v[110:111]
	v_pk_add_f32 v[72:73], v[72:73], v[112:113]
	s_waitcnt vmcnt(13)
	v_pk_add_f32 v[70:71], v[70:71], v[114:115]
	v_pk_add_f32 v[72:73], v[72:73], v[116:117]
	s_waitcnt vmcnt(12)
	v_pk_add_f32 v[70:71], v[70:71], v[118:119]
	v_pk_add_f32 v[72:73], v[72:73], v[120:121]
	s_waitcnt vmcnt(11)
	v_pk_add_f32 v[70:71], v[70:71], v[122:123]
	v_pk_add_f32 v[72:73], v[72:73], v[124:125]
	global_load_dwordx4 v[82:85], v[78:79], off offset:2048
	global_load_dwordx4 v[86:89], v[80:81], off offset:2048
	global_load_dwordx4 v[90:93], v[134:135], off offset:2048
	global_load_dwordx4 v[94:97], v[136:137], off offset:2048
	global_load_dwordx4 v[98:101], v[138:139], off offset:2048
	global_load_dwordx4 v[102:105], v[140:141], off offset:2048
	global_load_dwordx4 v[106:109], v[174:175], off offset:2048
	global_load_dwordx4 v[110:113], v[176:177], off offset:2048
	global_load_dwordx4 v[114:117], v[178:179], off offset:2048
	global_load_dwordx4 v[118:121], v[180:181], off offset:2048
	global_load_dwordx4 v[122:125], v[182:183], off offset:2048
	s_waitcnt vmcnt(20)
	v_pk_add_f32 v[74:75], v[74:75], v[184:185]
	v_pk_add_f32 v[76:77], v[76:77], v[186:187]
	s_waitcnt vmcnt(19)
; __device__ __forceinline__ void row_pass(const Params& P, int l, int mode, LAS float* pl) {
;     ...
;                     const int nsl = (mode == 1) ? 3 : 11;
; #pragma unroll
;                     for (int j = 0; j < 4; ++j) { const float* yq = y32 + (size_t)(b * CTXL + (w - SEQ)) * DM + 4 * lane + 256 * j; f32x4 a = *(const f32x4*)yq;
;                         for (int sl = 1; sl < nsl; ++sl) a = a + *(const f32x4*)(yq + (size_t)sl * 512 * DM);
;                         yv[r][j] = a; }
	v_pk_add_f32 v[74:75], v[74:75], v[188:189]
	v_pk_add_f32 v[76:77], v[76:77], v[190:191]
	s_waitcnt vmcnt(18)
	v_pk_add_f32 v[74:75], v[74:75], v[198:199]
	v_pk_add_f32 v[76:77], v[76:77], v[200:201]
	s_waitcnt vmcnt(17)
	v_pk_add_f32 v[74:75], v[74:75], v[202:203]
	v_pk_add_f32 v[76:77], v[76:77], v[204:205]
	s_waitcnt vmcnt(16)
	v_pk_add_f32 v[74:75], v[74:75], v[206:207]
	v_pk_add_f32 v[76:77], v[76:77], v[208:209]
	s_waitcnt vmcnt(15)
	v_pk_add_f32 v[74:75], v[74:75], v[224:225]
	v_pk_add_f32 v[76:77], v[76:77], v[226:227]
	s_waitcnt vmcnt(14)
	v_pk_add_f32 v[74:75], v[74:75], v[228:229]
	v_pk_add_f32 v[76:77], v[76:77], v[230:231]
	s_waitcnt vmcnt(13)
	v_pk_add_f32 v[74:75], v[74:75], v[232:233]
	v_pk_add_f32 v[76:77], v[76:77], v[234:235]
	s_waitcnt vmcnt(12)
	v_pk_add_f32 v[74:75], v[74:75], v[236:237]
	v_pk_add_f32 v[76:77], v[76:77], v[238:239]
	s_waitcnt vmcnt(11)
	v_pk_add_f32 v[74:75], v[74:75], v[240:241]
	v_pk_add_f32 v[76:77], v[76:77], v[242:243]
	global_load_dwordx4 v[184:187], v[80:81], off offset:3072
	global_load_dwordx4 v[188:191], v[134:135], off offset:3072
	global_load_dwordx4 v[198:201], v[136:137], off offset:3072
	global_load_dwordx4 v[202:205], v[138:139], off offset:3072
	global_load_dwordx4 v[206:209], v[140:141], off offset:3072
	global_load_dwordx4 v[224:227], v[174:175], off offset:3072
	global_load_dwordx4 v[228:231], v[176:177], off offset:3072
	global_load_dwordx4 v[232:235], v[178:179], off offset:3072
	global_load_dwordx4 v[236:239], v[180:181], off offset:3072
	global_load_dwordx4 v[240:243], v[182:183], off offset:3072
	global_load_dwordx4 v[78:81], v[78:79], off offset:3072
	s_waitcnt vmcnt(20)
	v_pk_add_f32 v[82:83], v[82:83], v[86:87]
	v_pk_add_f32 v[84:85], v[84:85], v[88:89]
	s_waitcnt vmcnt(19)
	v_pk_add_f32 v[82:83], v[82:83], v[90:91]
	v_pk_add_f32 v[84:85], v[84:85], v[92:93]
	s_waitcnt vmcnt(18)
	v_pk_add_f32 v[82:83], v[82:83], v[94:95]
	v_pk_add_f32 v[84:85], v[84:85], v[96:97]
	s_waitcnt vmcnt(17)
	v_pk_add_f32 v[82:83], v[82:83], v[98:99]
	v_pk_add_f32 v[84:85], v[84:85], v[100:101]
	s_waitcnt vmcnt(16)
	v_pk_add_f32 v[82:83], v[82:83], v[102:103]
	v_pk_add_f32 v[84:85], v[84:85], v[104:105]
	s_waitcnt vmcnt(15)
	v_pk_add_f32 v[82:83], v[82:83], v[106:107]
	v_pk_add_f32 v[84:85], v[84:85], v[108:109]
	s_waitcnt vmcnt(14)
	v_pk_add_f32 v[82:83], v[82:83], v[110:111]
	v_pk_add_f32 v[84:85], v[84:85], v[112:113]
	s_waitcnt vmcnt(13)
	v_pk_add_f32 v[82:83], v[82:83], v[114:115]
	v_pk_add_f32 v[84:85], v[84:85], v[116:117]
	s_waitcnt vmcnt(12)
	v_pk_add_f32 v[82:83], v[82:83], v[118:119]
	v_pk_add_f32 v[84:85], v[84:85], v[120:121]
	s_waitcnt vmcnt(11)
	v_pk_add_f32 v[82:83], v[82:83], v[122:123]
	v_pk_add_f32 v[84:85], v[84:85], v[124:125]
	s_waitcnt vmcnt(0)
	v_pk_add_f32 v[78:79], v[78:79], v[184:185]
	v_pk_add_f32 v[80:81], v[80:81], v[186:187]
	s_waitcnt vmcnt(0)
	v_pk_add_f32 v[78:79], v[78:79], v[188:189]
	v_pk_add_f32 v[80:81], v[80:81], v[190:191]
	s_waitcnt vmcnt(0)
	v_pk_add_f32 v[78:79], v[78:79], v[198:199]
	v_pk_add_f32 v[80:81], v[80:81], v[200:201]
	s_waitcnt vmcnt(0)
	v_pk_add_f32 v[78:79], v[78:79], v[202:203]
	v_pk_add_f32 v[80:81], v[80:81], v[204:205]
	s_waitcnt vmcnt(0)
	v_pk_add_f32 v[78:79], v[78:79], v[206:207]
	v_pk_add_f32 v[80:81], v[80:81], v[208:209]
	s_waitcnt vmcnt(0)
	v_pk_add_f32 v[78:79], v[78:79], v[224:225]
	v_pk_add_f32 v[80:81], v[80:81], v[226:227]
	s_waitcnt vmcnt(0)
	v_pk_add_f32 v[78:79], v[78:79], v[228:229]
	v_pk_add_f32 v[80:81], v[80:81], v[230:231]
	s_waitcnt vmcnt(0)
	v_pk_add_f32 v[78:79], v[78:79], v[232:233]
	v_pk_add_f32 v[80:81], v[80:81], v[234:235]
	s_waitcnt vmcnt(0)
	v_pk_add_f32 v[78:79], v[78:79], v[236:237]
	v_pk_add_f32 v[80:81], v[80:81], v[238:239]
	s_waitcnt vmcnt(0)
	v_pk_add_f32 v[78:79], v[78:79], v[240:241]
	v_pk_add_f32 v[80:81], v[80:81], v[242:243]

; __device__ __forceinline__ void row_pass(const Params& P, int l, int mode, LAS float* pl) {
;     ...
;                     const int nsl = (mode == 1) ? 3 : 11;
; #pragma unroll
;                     for (int j = 0; j < 4; ++j) { const float* yq = y32 + (size_t)(b * CTXL + (w - SEQ)) * DM + 4 * lane + 256 * j; f32x4 a = *(const f32x4*)yq;
;                         for (int sl = 1; sl < nsl; ++sl) a = a + *(const f32x4*)(yq + (size_t)sl * 512 * DM);
;                         yv[r][j] = a; }
.LBB0_1301:
	s_cmpk_lt_i32 s22, 0x2000
	s_cselect_b64 s[10:11], -1, 0
	s_mov_b64 s[18:19], -1
	s_and_b64 vcc, exec, s[10:11]
	s_cbranch_vccnz .LBB0_1303
	s_lshl_b32 s18, s26, 8
	s_add_i32 s18, s22, s18
	s_addk_i32 s18, 0xe000
	s_ashr_i32 s19, s18, 31
	s_lshl_b64 s[18:19], s[18:19], 12
	v_lshl_add_u64 v[138:139], v[144:145], 0, s[18:19]
	s_mov_b64 s[18:19], 0
	v_lshl_add_u64 v[140:141], v[138:139], 0, s[100:101]
	v_lshl_add_u64 v[174:175], v[140:141], 0, s[100:101]
	v_lshl_add_u64 v[176:177], v[174:175], 0, s[100:101]
	v_lshl_add_u64 v[178:179], v[176:177], 0, s[100:101]
	v_lshl_add_u64 v[180:181], v[178:179], 0, s[100:101]
	v_lshl_add_u64 v[182:183], v[180:181], 0, s[100:101]
	v_lshl_add_u64 v[184:185], v[182:183], 0, s[100:101]
	v_lshl_add_u64 v[186:187], v[184:185], 0, s[100:101]
	v_lshl_add_u64 v[188:189], v[186:187], 0, s[100:101]
	v_lshl_add_u64 v[190:191], v[188:189], 0, s[100:101]
	global_load_dwordx4 v[86:89], v[138:139], off
	global_load_dwordx4 v[98:101], v[140:141], off
	global_load_dwordx4 v[102:105], v[174:175], off
	global_load_dwordx4 v[106:109], v[176:177], off
	global_load_dwordx4 v[110:113], v[178:179], off
	global_load_dwordx4 v[114:117], v[180:181], off
	global_load_dwordx4 v[118:121], v[182:183], off
	global_load_dwordx4 v[122:125], v[184:185], off
	global_load_dwordx4 v[126:129], v[186:187], off
	global_load_dwordx4 v[130:133], v[188:189], off
	global_load_dwordx4 v[134:137], v[190:191], off
	global_load_dwordx4 v[90:93], v[138:139], off offset:1024
	global_load_dwordx4 v[198:201], v[140:141], off offset:1024
	global_load_dwordx4 v[202:205], v[174:175], off offset:1024
	global_load_dwordx4 v[206:209], v[176:177], off offset:1024
	global_load_dwordx4 v[224:227], v[178:179], off offset:1024
	global_load_dwordx4 v[228:231], v[180:181], off offset:1024
	global_load_dwordx4 v[232:235], v[182:183], off offset:1024
	global_load_dwordx4 v[236:239], v[184:185], off offset:1024
	global_load_dwordx4 v[240:243], v[186:187], off offset:1024
	global_load_dwordx4 v[244:247], v[188:189], off offset:1024
	global_load_dwordx4 v[248:251], v[190:191], off offset:1024
	s_waitcnt vmcnt(20)
	v_pk_add_f32 v[86:87], v[86:87], v[98:99]
	v_pk_add_f32 v[88:89], v[88:89], v[100:101]
	s_waitcnt vmcnt(19)
	v_pk_add_f32 v[86:87], v[86:87], v[102:103]
	v_pk_add_f32 v[88:89], v[88:89], v[104:105]
	s_waitcnt vmcnt(18)
	v_pk_add_f32 v[86:87], v[86:87], v[106:107]
	v_pk_add_f32 v[88:89], v[88:89], v[108:109]
	s_waitcnt vmcnt(17)
	v_pk_add_f32 v[86:87], v[86:87], v[110:111]
	v_pk_add_f32 v[88:89], v[88:89], v[112:113]
	s_waitcnt vmcnt(16)
	v_pk_add_f32 v[86:87], v[86:87], v[114:115]
	v_pk_add_f32 v[88:89], v[88:89], v[116:117]
	s_waitcnt vmcnt(15)
	v_pk_add_f32 v[86:87], v[86:87], v[118:119]
	v_pk_add_f32 v[88:89], v[88:89], v[120:121]
	s_waitcnt vmcnt(14)
	v_pk_add_f32 v[86:87], v[86:87], v[122:123]
	v_pk_add_f32 v[88:89], v[88:89], v[124:125]
	s_waitcnt vmcnt(13)
	v_pk_add_f32 v[86:87], v[86:87], v[126:127]
	v_pk_add_f32 v[88:89], v[88:89], v[128:129]
	s_waitcnt vmcnt(12)
	v_pk_add_f32 v[86:87], v[86:87], v[130:131]
	v_pk_add_f32 v[88:89], v[88:89], v[132:133]
	s_waitcnt vmcnt(11)
	v_pk_add_f32 v[86:87], v[86:87], v[134:135]
	v_pk_add_f32 v[88:89], v[88:89], v[136:137]
	global_load_dwordx4 v[94:97], v[138:139], off offset:2048
	global_load_dwordx4 v[98:101], v[140:141], off offset:2048
	global_load_dwordx4 v[102:105], v[174:175], off offset:2048
	global_load_dwordx4 v[106:109], v[176:177], off offset:2048
	global_load_dwordx4 v[110:113], v[178:179], off offset:2048
	global_load_dwordx4 v[114:117], v[180:181], off offset:2048
	global_load_dwordx4 v[118:121], v[182:183], off offset:2048
	global_load_dwordx4 v[122:125], v[184:185], off offset:2048
	global_load_dwordx4 v[126:129], v[186:187], off offset:2048
	global_load_dwordx4 v[130:133], v[188:189], off offset:2048
	global_load_dwordx4 v[134:137], v[190:191], off offset:2048
	s_waitcnt vmcnt(20)
	v_pk_add_f32 v[90:91], v[90:91], v[198:199]
	v_pk_add_f32 v[92:93], v[92:93], v[200:201]
	s_waitcnt vmcnt(19)
; __device__ __forceinline__ void row_pass(const Params& P, int l, int mode, LAS float* pl) {
;     ...
;                     const int nsl = (mode == 1) ? 3 : 11;
; #pragma unroll
;                     for (int j = 0; j < 4; ++j) { const float* yq = y32 + (size_t)(b * CTXL + (w - SEQ)) * DM + 4 * lane + 256 * j; f32x4 a = *(const f32x4*)yq;
;                         for (int sl = 1; sl < nsl; ++sl) a = a + *(const f32x4*)(yq + (size_t)sl * 512 * DM);
;                         yv[r][j] = a; }
	v_pk_add_f32 v[90:91], v[90:91], v[202:203]
	v_pk_add_f32 v[92:93], v[92:93], v[204:205]
	s_waitcnt vmcnt(18)
	v_pk_add_f32 v[90:91], v[90:91], v[206:207]
	v_pk_add_f32 v[92:93], v[92:93], v[208:209]
	s_waitcnt vmcnt(17)
	v_pk_add_f32 v[90:91], v[90:91], v[224:225]
	v_pk_add_f32 v[92:93], v[92:93], v[226:227]
	s_waitcnt vmcnt(16)
	v_pk_add_f32 v[90:91], v[90:91], v[228:229]
	v_pk_add_f32 v[92:93], v[92:93], v[230:231]
	s_waitcnt vmcnt(15)
	v_pk_add_f32 v[90:91], v[90:91], v[232:233]
	v_pk_add_f32 v[92:93], v[92:93], v[234:235]
	s_waitcnt vmcnt(14)
	v_pk_add_f32 v[90:91], v[90:91], v[236:237]
	v_pk_add_f32 v[92:93], v[92:93], v[238:239]
	s_waitcnt vmcnt(13)
	v_pk_add_f32 v[90:91], v[90:91], v[240:241]
	v_pk_add_f32 v[92:93], v[92:93], v[242:243]
	s_waitcnt vmcnt(12)
	v_pk_add_f32 v[90:91], v[90:91], v[244:245]
	v_pk_add_f32 v[92:93], v[92:93], v[246:247]
	s_waitcnt vmcnt(11)
	v_pk_add_f32 v[90:91], v[90:91], v[248:249]
	v_pk_add_f32 v[92:93], v[92:93], v[250:251]
	global_load_dwordx4 v[198:201], v[140:141], off offset:3072
	global_load_dwordx4 v[202:205], v[174:175], off offset:3072
	global_load_dwordx4 v[206:209], v[176:177], off offset:3072
	global_load_dwordx4 v[224:227], v[178:179], off offset:3072
	global_load_dwordx4 v[228:231], v[180:181], off offset:3072
	global_load_dwordx4 v[232:235], v[182:183], off offset:3072
	global_load_dwordx4 v[236:239], v[184:185], off offset:3072
	global_load_dwordx4 v[240:243], v[186:187], off offset:3072
	global_load_dwordx4 v[244:247], v[188:189], off offset:3072
	global_load_dwordx4 v[248:251], v[190:191], off offset:3072
	global_load_dwordx4 v[138:141], v[138:139], off offset:3072
	s_waitcnt vmcnt(20)
	v_pk_add_f32 v[94:95], v[94:95], v[98:99]
	v_pk_add_f32 v[96:97], v[96:97], v[100:101]
	s_waitcnt vmcnt(19)
	v_pk_add_f32 v[94:95], v[94:95], v[102:103]
	v_pk_add_f32 v[96:97], v[96:97], v[104:105]
	s_waitcnt vmcnt(18)
	v_pk_add_f32 v[94:95], v[94:95], v[106:107]
	v_pk_add_f32 v[96:97], v[96:97], v[108:109]
	s_waitcnt vmcnt(17)
	v_pk_add_f32 v[94:95], v[94:95], v[110:111]
	v_pk_add_f32 v[96:97], v[96:97], v[112:113]
	s_waitcnt vmcnt(16)
	v_pk_add_f32 v[94:95], v[94:95], v[114:115]
	v_pk_add_f32 v[96:97], v[96:97], v[116:117]
	s_waitcnt vmcnt(15)
	v_pk_add_f32 v[94:95], v[94:95], v[118:119]
	v_pk_add_f32 v[96:97], v[96:97], v[120:121]
	s_waitcnt vmcnt(14)
	v_pk_add_f32 v[94:95], v[94:95], v[122:123]
	v_pk_add_f32 v[96:97], v[96:97], v[124:125]
	s_waitcnt vmcnt(13)
	v_pk_add_f32 v[94:95], v[94:95], v[126:127]
	v_pk_add_f32 v[96:97], v[96:97], v[128:129]
	s_waitcnt vmcnt(12)
	v_pk_add_f32 v[94:95], v[94:95], v[130:131]
	v_pk_add_f32 v[96:97], v[96:97], v[132:133]
	s_waitcnt vmcnt(11)
	v_pk_add_f32 v[94:95], v[94:95], v[134:135]
	v_pk_add_f32 v[96:97], v[96:97], v[136:137]
	s_waitcnt vmcnt(0)
	v_pk_add_f32 v[138:139], v[138:139], v[198:199]
	v_pk_add_f32 v[140:141], v[140:141], v[200:201]
	s_waitcnt vmcnt(0)
	v_pk_add_f32 v[138:139], v[138:139], v[202:203]
	v_pk_add_f32 v[140:141], v[140:141], v[204:205]
	s_waitcnt vmcnt(0)
	v_pk_add_f32 v[138:139], v[138:139], v[206:207]
	v_pk_add_f32 v[140:141], v[140:141], v[208:209]
	s_waitcnt vmcnt(0)
	v_pk_add_f32 v[138:139], v[138:139], v[224:225]
	v_pk_add_f32 v[140:141], v[140:141], v[226:227]
	s_waitcnt vmcnt(0)
	v_pk_add_f32 v[138:139], v[138:139], v[228:229]
	v_pk_add_f32 v[140:141], v[140:141], v[230:231]
	s_waitcnt vmcnt(0)
	v_pk_add_f32 v[138:139], v[138:139], v[232:233]
	v_pk_add_f32 v[140:141], v[140:141], v[234:235]
	s_waitcnt vmcnt(0)
	v_pk_add_f32 v[138:139], v[138:139], v[236:237]
	v_pk_add_f32 v[140:141], v[140:141], v[238:239]
	s_waitcnt vmcnt(0)
	v_pk_add_f32 v[138:139], v[138:139], v[240:241]
	v_pk_add_f32 v[140:141], v[140:141], v[242:243]
	s_waitcnt vmcnt(0)
	v_pk_add_f32 v[138:139], v[138:139], v[244:245]
	v_pk_add_f32 v[140:141], v[140:141], v[246:247]
	s_waitcnt vmcnt(0)
	v_pk_add_f32 v[138:139], v[138:139], v[248:249]
	v_pk_add_f32 v[140:141], v[140:141], v[250:251]

; __global__ void __launch_bounds__(NTHREADS, 2) mega_fwd(Params P) {
	.amdhsa_kernel _Z8mega_fwd6Params
		.amdhsa_group_segment_fixed_size 0
		.amdhsa_private_segment_fixed_size 0
		.amdhsa_kernarg_size 440
		.amdhsa_user_sgpr_count 2
		.amdhsa_user_sgpr_dispatch_ptr 0
		.amdhsa_user_sgpr_queue_ptr 0
		.amdhsa_user_sgpr_kernarg_segment_ptr 1
		.amdhsa_user_sgpr_dispatch_id 0
		.amdhsa_user_sgpr_kernarg_preload_length 0
		.amdhsa_user_sgpr_kernarg_preload_offset 0
		.amdhsa_user_sgpr_private_segment_size 0
		.amdhsa_uses_dynamic_stack 0
		.amdhsa_enable_private_segment 0
		.amdhsa_system_sgpr_workgroup_id_x 1
		.amdhsa_system_sgpr_workgroup_id_y 0
		.amdhsa_system_sgpr_workgroup_id_z 0
		.amdhsa_system_sgpr_workgroup_info 0
		.amdhsa_system_vgpr_workitem_id 2
		.amdhsa_next_free_vgpr 255
		.amdhsa_next_free_sgpr 102
		.amdhsa_accum_offset 256
		.amdhsa_reserve_vcc 1
		.amdhsa_float_round_mode_32 0
		.amdhsa_float_round_mode_16_64 0
		.amdhsa_float_denorm_mode_32 3
		.amdhsa_float_denorm_mode_16_64 3
		.amdhsa_dx10_clamp 1
		.amdhsa_ieee_mode 1
		.amdhsa_fp16_overflow 0
		.amdhsa_tg_split 0
		.amdhsa_exception_fp_ieee_invalid_op 0
		.amdhsa_exception_fp_denorm_src 0
		.amdhsa_exception_fp_ieee_div_zero 0
		.amdhsa_exception_fp_ieee_overflow 0
		.amdhsa_exception_fp_ieee_underflow 0
		.amdhsa_exception_fp_ieee_inexact 0
		.amdhsa_exception_int_div_zero 0
	.end_amdhsa_kernel

; __global__ void __launch_bounds__(NTHREADS, 2) mega_fwd(Params P) {
amdhsa.kernels:
  - .agpr_count:     0
    .args:
      - .offset:         0
        .size:           184
        .value_kind:     by_value
      - .offset:         184
        .size:           4
        .value_kind:     hidden_block_count_x
      - .offset:         188
        .size:           4
        .value_kind:     hidden_block_count_y
      - .offset:         192
        .size:           4
        .value_kind:     hidden_block_count_z
      - .offset:         196
        .size:           2
        .value_kind:     hidden_group_size_x
      - .offset:         198
        .size:           2
        .value_kind:     hidden_group_size_y
      - .offset:         200
        .size:           2
        .value_kind:     hidden_group_size_z
      - .offset:         202
        .size:           2
        .value_kind:     hidden_remainder_x
      - .offset:         204
        .size:           2
        .value_kind:     hidden_remainder_y
      - .offset:         206
        .size:           2
        .value_kind:     hidden_remainder_z
      - .offset:         224
        .size:           8
        .value_kind:     hidden_global_offset_x
      - .offset:         232
        .size:           8
        .value_kind:     hidden_global_offset_y
      - .offset:         240
        .size:           8
        .value_kind:     hidden_global_offset_z
      - .offset:         248
        .size:           2
        .value_kind:     hidden_grid_dims
      - .offset:         272
        .size:           8
        .value_kind:     hidden_multigrid_sync_arg
      - .offset:         304
        .size:           4
        .value_kind:     hidden_dynamic_lds_size
    .group_segment_fixed_size: 0
    .kernarg_segment_align: 8
    .kernarg_segment_size: 440
    .language:       OpenCL C
    .language_version:
      - 2
      - 0
    .max_flat_workgroup_size: 512
    .name:           _Z8mega_fwd6Params
    .private_segment_fixed_size: 0
    .sgpr_count:     108
    .sgpr_spill_count: 189
    .symbol:         _Z8mega_fwd6Params.kd
    .uniform_work_group_size: 1
    .uses_dynamic_stack: false
    .vgpr_count:     255
    .vgpr_spill_count: 0
    .wavefront_size: 64
